# v62 + P5: 6 of the 16 Z stores per wave deferred into the next unit's first two MMA blocks (between MFMAs), waits 18/20/14/12
# speedup vs baseline: 1.0067x; 1.0067x over previous
; #define PG8_STAGE(bufoff, gbase, voff) do { _Pragma("unroll") for (int _i = 0; _i < 2; ++_i) \
;         __builtin_amdgcn_global_load_lds((const unsigned*)((const char*)(gbase) + (voff)[_i]), (PG8_LAS unsigned*)(lds + (bufoff) + ldsw + _i * 8192), 16, 0, 0); } while (0)
; #define PG8_LDA(dst, b, h) do { _Pragma("unroll") for (int m = 0; m < 4; ++m) _Pragma("unroll") for (int k = 0; k < 2; ++k) dst[m][k] = *(const PG8_LAS bf16x8*)(lds + PG8_SA(b, h) + aoff + m * 2048 + k * 1024); } while (0)
; #define PG8_MMA(ai, bj, At, Bt) do { __builtin_amdgcn_s_setprio(1); _Pragma("unroll") for (int m = 0; m < 4; ++m) _Pragma("unroll") for (int n = 0; n < 2; ++n) _Pragma("unroll") for (int k = 0; k < 2; ++k) \
;         acc[ai][bj][m][n] = __builtin_amdgcn_mfma_f32_16x16x32_bf16(Bt[n][k], At[m][k], acc[ai][bj][m][n], 0, 0, 0); __builtin_amdgcn_s_setprio(0); } while (0)
; #define PG8_WAIT_V(n) asm volatile("s_waitcnt vmcnt(" #n ")" ::: "memory")
; #define PG8_WAIT_L(n) asm volatile("s_waitcnt lgkmcnt(" #n ")" ::: "memory")
; #define PG8_BAR __builtin_amdgcn_s_barrier()
; #define PG8_SCHED __builtin_amdgcn_sched_barrier(0)
; template <class Epi, class Sched, bool ALIGN_EPI = false, bool SP2 = false>
; __device__ __forceinline__ void gemm_phase(PG8_LAS unsigned char* lds, const Gemm g, const Sched& S, const Epi& E) {
;     ...
;             PG8_WAIT_V(8); PG8_WAIT_L(0); PG8_BAR; PG8_MMA(0, 0, At, B0); PG8_MMA(0, 1, At, B1); PG8_BAR; PG8_SCHED;
;             PG8_LDA(At, 0, 1); PG8_STAGE(PG8_SB(0, 0), b2, voffB); PG8_STAGE(PG8_SB(0, 1), b2 + hstep, voffB); PG8_STAGE(PG8_SA(0, 0), a2, voffA);
;             PG8_WAIT_V(8); PG8_WAIT_L(0); PG8_BAR; PG8_MMA(1, 0, At, B0); PG8_MMA(1, 1, At, B1); PG8_BAR; PG8_SCHED;
.Lrw_P5_0:
	s_waitcnt vmcnt(18)
.Lrj_P5_0:
	s_waitcnt lgkmcnt(0)
	s_barrier
	s_setprio 1
	s_waitcnt lgkmcnt(0)
	v_mfma_f32_16x16x32_bf16 v[124:127], v[144:147], v[184:187], v[124:127]
	v_mfma_f32_16x16x32_bf16 v[120:123], v[160:163], v[184:187], v[120:123]
	v_mfma_f32_16x16x32_bf16 v[108:111], v[144:147], v[192:195], v[108:111]
	v_mfma_f32_16x16x32_bf16 v[104:107], v[160:163], v[192:195], v[104:107]
	v_mfma_f32_16x16x32_bf16 v[92:95], v[144:147], v[200:203], v[92:95]
	v_mfma_f32_16x16x32_bf16 v[88:91], v[160:163], v[200:203], v[88:91]
	v_mfma_f32_16x16x32_bf16 v[76:79], v[144:147], v[208:211], v[76:79]
	v_mfma_f32_16x16x32_bf16 v[72:75], v[160:163], v[208:211], v[72:75]
	s_cmp_eq_u32 s99, 1
	s_cbranch_scc0 .Lndm_P5_0
	global_store_dwordx4 v227, v[228:231], s[72:73]
.Lndm_P5_0:
	v_mfma_f32_16x16x32_bf16 v[124:127], v[156:159], v[188:191], v[124:127]
	v_mfma_f32_16x16x32_bf16 v[120:123], v[164:167], v[188:191], v[120:123]
	v_mfma_f32_16x16x32_bf16 v[108:111], v[156:159], v[196:199], v[108:111]
	v_mfma_f32_16x16x32_bf16 v[104:107], v[164:167], v[196:199], v[104:107]
	v_mfma_f32_16x16x32_bf16 v[92:95], v[156:159], v[204:207], v[92:95]
	v_mfma_f32_16x16x32_bf16 v[88:91], v[164:167], v[204:207], v[88:91]
	v_mfma_f32_16x16x32_bf16 v[76:79], v[156:159], v[212:215], v[76:79]
	v_mfma_f32_16x16x32_bf16 v[72:75], v[164:167], v[212:215], v[72:75]
	s_setprio 0
	s_setprio 1
	v_mfma_f32_16x16x32_bf16 v[116:119], v[168:171], v[184:187], v[116:119]
	v_mfma_f32_16x16x32_bf16 v[112:115], v[176:179], v[184:187], v[112:115]
	v_mfma_f32_16x16x32_bf16 v[100:103], v[168:171], v[192:195], v[100:103]
	v_mfma_f32_16x16x32_bf16 v[96:99], v[176:179], v[192:195], v[96:99]
	v_mfma_f32_16x16x32_bf16 v[84:87], v[168:171], v[200:203], v[84:87]
	v_mfma_f32_16x16x32_bf16 v[80:83], v[176:179], v[200:203], v[80:83]
	v_mfma_f32_16x16x32_bf16 v[68:71], v[168:171], v[208:211], v[68:71]
	v_mfma_f32_16x16x32_bf16 v[64:67], v[176:179], v[208:211], v[64:67]
	s_cmp_eq_u32 s99, 1
	s_cbranch_scc0 .Lndm_P5_1
	global_store_dwordx4 v227, v[232:235], s[72:73] offset:256
.Lndm_P5_1:
	v_mfma_f32_16x16x32_bf16 v[116:119], v[172:175], v[188:191], v[116:119]
	v_mfma_f32_16x16x32_bf16 v[112:115], v[180:183], v[188:191], v[112:115]
	v_mfma_f32_16x16x32_bf16 v[100:103], v[172:175], v[196:199], v[100:103]
	v_mfma_f32_16x16x32_bf16 v[96:99], v[180:183], v[196:199], v[96:99]
	v_mfma_f32_16x16x32_bf16 v[84:87], v[172:175], v[204:207], v[84:87]
	v_mfma_f32_16x16x32_bf16 v[80:83], v[180:183], v[204:207], v[80:83]
	v_mfma_f32_16x16x32_bf16 v[68:71], v[172:175], v[212:215], v[68:71]
	v_mfma_f32_16x16x32_bf16 v[64:67], v[180:183], v[212:215], v[64:67]
	s_setprio 0
	s_barrier
	s_add_i32 s66, s52, s39
	v_lshl_add_u64 v[216:217], s[34:35], 0, v[132:133]
	s_mov_b32 m0, s66
	ds_read_b128 v[184:187], v153 offset:16384
	ds_read_b128 v[188:191], v153 offset:17408
	ds_read_b128 v[192:195], v153 offset:18432
	ds_read_b128 v[196:199], v153 offset:19456
	ds_read_b128 v[200:203], v153 offset:20480
	ds_read_b128 v[204:207], v153 offset:21504
	ds_read_b128 v[208:211], v153 offset:22528
	ds_read_b128 v[212:215], v153 offset:23552
	global_load_lds_dwordx4 v[216:217], off
	s_add_i32 m0, s66, 0x2000
	s_add_u32 s66, s34, 0x40000
	v_lshl_add_u64 v[218:219], s[34:35], 0, v[128:129]
	s_addc_u32 s67, s35, 0
	s_add_i32 s68, s53, s39
	global_load_lds_dwordx4 v[218:219], off
	v_lshl_add_u64 v[220:221], s[66:67], 0, v[132:133]
	s_mov_b32 m0, s68
	v_lshl_add_u64 v[222:223], s[36:37], 0, v[130:131]
	global_load_lds_dwordx4 v[220:221], off
	v_lshl_add_u64 v[220:221], s[66:67], 0, v[128:129]
	s_add_i32 m0, s68, 0x2000
	s_nop 0
	global_load_lds_dwordx4 v[220:221], off
	v_lshl_add_u64 v[220:221], s[36:37], 0, v[134:135]
	s_mov_b32 m0, s29
	s_nop 0
	global_load_lds_dwordx4 v[220:221], off
	s_mov_b32 m0, s42
	s_nop 0
	global_load_lds_dwordx4 v[222:223], off
	s_cmp_eq_u32 s99, 1
	s_cbranch_scc1 .Lrw_P5_1
	s_waitcnt vmcnt(8)
	s_branch .Lrj_P5_1

; #define PG8_STAGE(bufoff, gbase, voff) do { _Pragma("unroll") for (int _i = 0; _i < 2; ++_i) \
;         __builtin_amdgcn_global_load_lds((const unsigned*)((const char*)(gbase) + (voff)[_i]), (PG8_LAS unsigned*)(lds + (bufoff) + ldsw + _i * 8192), 16, 0, 0); } while (0)
; #define PG8_LDA(dst, b, h) do { _Pragma("unroll") for (int m = 0; m < 4; ++m) _Pragma("unroll") for (int k = 0; k < 2; ++k) dst[m][k] = *(const PG8_LAS bf16x8*)(lds + PG8_SA(b, h) + aoff + m * 2048 + k * 1024); } while (0)
; #define PG8_LDB(dst, b, h) do { _Pragma("unroll") for (int n = 0; n < 2; ++n) _Pragma("unroll") for (int k = 0; k < 2; ++k) dst[n][k] = *(const PG8_LAS bf16x8*)(lds + PG8_SB(b, h) + boff + n * 2048 + k * 1024); } while (0)
; #define PG8_MMA(ai, bj, At, Bt) do { __builtin_amdgcn_s_setprio(1); _Pragma("unroll") for (int m = 0; m < 4; ++m) _Pragma("unroll") for (int n = 0; n < 2; ++n) _Pragma("unroll") for (int k = 0; k < 2; ++k) \
;         acc[ai][bj][m][n] = __builtin_amdgcn_mfma_f32_16x16x32_bf16(Bt[n][k], At[m][k], acc[ai][bj][m][n], 0, 0, 0); __builtin_amdgcn_s_setprio(0); } while (0)
; #define PG8_WAIT_V(n) asm volatile("s_waitcnt vmcnt(" #n ")" ::: "memory")
; #define PG8_WAIT_L(n) asm volatile("s_waitcnt lgkmcnt(" #n ")" ::: "memory")
; #define PG8_BAR __builtin_amdgcn_s_barrier()
; #define PG8_SCHED __builtin_amdgcn_sched_barrier(0)
; template <class Epi, class Sched, bool ALIGN_EPI = false, bool SP2 = false>
; __device__ __forceinline__ void gemm_phase(PG8_LAS unsigned char* lds, const Gemm g, const Sched& S, const Epi& E) {
;     ...
;             PG8_WAIT_V(8); PG8_WAIT_L(0); PG8_BAR; PG8_MMA(1, 0, At, B0); PG8_MMA(1, 1, At, B1); PG8_BAR; PG8_SCHED;
;             PG8_LDB(B0, 1, 0); PG8_LDB(B1, 1, 1); PG8_SCHED; PG8_LDA(At, 1, 0); PG8_STAGE(PG8_SA(0, 1), a2 + hstep, voffA);
;             PG8_WAIT_V(8); PG8_WAIT_L(0); PG8_BAR; PG8_MMA(0, 0, At, B0); PG8_MMA(0, 1, At, B1); PG8_BAR; PG8_SCHED;
.Lrj_P5_1:
	s_waitcnt lgkmcnt(0)
	s_barrier
	s_setprio 1
	s_waitcnt lgkmcnt(0)
	v_mfma_f32_16x16x32_bf16 v[60:63], v[144:147], v[184:187], v[60:63]
	v_mfma_f32_16x16x32_bf16 v[56:59], v[160:163], v[184:187], v[56:59]
	v_mfma_f32_16x16x32_bf16 v[44:47], v[144:147], v[192:195], v[44:47]
	v_mfma_f32_16x16x32_bf16 v[40:43], v[160:163], v[192:195], v[40:43]
	s_cmp_eq_u32 s99, 1
	s_cbranch_scc0 .Lndm_P5_2
	global_store_dwordx4 v227, v[236:239], s[74:75]
.Lndm_P5_2:
	v_mfma_f32_16x16x32_bf16 v[28:31], v[144:147], v[200:203], v[28:31]
	v_mfma_f32_16x16x32_bf16 v[24:27], v[160:163], v[200:203], v[24:27]
	v_mfma_f32_16x16x32_bf16 v[12:15], v[144:147], v[208:211], v[12:15]
	v_mfma_f32_16x16x32_bf16 v[8:11], v[160:163], v[208:211], v[8:11]
	v_mfma_f32_16x16x32_bf16 v[60:63], v[156:159], v[188:191], v[60:63]
	v_mfma_f32_16x16x32_bf16 v[56:59], v[164:167], v[188:191], v[56:59]
	v_mfma_f32_16x16x32_bf16 v[44:47], v[156:159], v[196:199], v[44:47]
	v_mfma_f32_16x16x32_bf16 v[40:43], v[164:167], v[196:199], v[40:43]
	s_cmp_eq_u32 s99, 1
	s_cbranch_scc0 .Lndm_P5_3
	global_store_dwordx4 v227, v[240:243], s[74:75] offset:256
.Lndm_P5_3:
	v_mfma_f32_16x16x32_bf16 v[28:31], v[156:159], v[204:207], v[28:31]
	v_mfma_f32_16x16x32_bf16 v[24:27], v[164:167], v[204:207], v[24:27]
	v_mfma_f32_16x16x32_bf16 v[12:15], v[156:159], v[212:215], v[12:15]
	v_mfma_f32_16x16x32_bf16 v[8:11], v[164:167], v[212:215], v[8:11]
	s_setprio 0
	s_setprio 1
	v_mfma_f32_16x16x32_bf16 v[52:55], v[168:171], v[184:187], v[52:55]
	v_mfma_f32_16x16x32_bf16 v[48:51], v[176:179], v[184:187], v[48:51]
	v_mfma_f32_16x16x32_bf16 v[36:39], v[168:171], v[192:195], v[36:39]
	v_mfma_f32_16x16x32_bf16 v[32:35], v[176:179], v[192:195], v[32:35]
	s_cmp_eq_u32 s99, 1
	s_cbranch_scc0 .Lndm_P5_4
	global_store_dwordx4 v227, v[244:247], s[76:77]
.Lndm_P5_4:
	v_mfma_f32_16x16x32_bf16 v[20:23], v[168:171], v[200:203], v[20:23]
	v_mfma_f32_16x16x32_bf16 v[16:19], v[176:179], v[200:203], v[16:19]
	v_mfma_f32_16x16x32_bf16 v[4:7], v[168:171], v[208:211], v[4:7]
	v_mfma_f32_16x16x32_bf16 v[0:3], v[176:179], v[208:211], v[0:3]
	v_mfma_f32_16x16x32_bf16 v[52:55], v[172:175], v[188:191], v[52:55]
	v_mfma_f32_16x16x32_bf16 v[48:51], v[180:183], v[188:191], v[48:51]
	v_mfma_f32_16x16x32_bf16 v[36:39], v[172:175], v[196:199], v[36:39]
	v_mfma_f32_16x16x32_bf16 v[32:35], v[180:183], v[196:199], v[32:35]
	s_cmp_eq_u32 s99, 1
	s_cbranch_scc0 .Lndm_P5_5
	global_store_dwordx4 v227, v[248:251], s[76:77] offset:256
.Lndm_P5_5:
	v_mfma_f32_16x16x32_bf16 v[20:23], v[172:175], v[204:207], v[20:23]
	v_mfma_f32_16x16x32_bf16 v[16:19], v[180:183], v[204:207], v[16:19]
	v_mfma_f32_16x16x32_bf16 v[4:7], v[172:175], v[212:215], v[4:7]
	v_mfma_f32_16x16x32_bf16 v[0:3], v[180:183], v[212:215], v[0:3]
	s_setprio 0
	s_barrier
	s_add_i32 s66, 0, 0x18000
	v_add_u32_e32 v155, s66, v149
	s_add_i32 s67, 0, 0x1c000
	ds_read_b128 v[144:147], v155
	ds_read_b128 v[156:159], v155 offset:1024
	ds_read_b128 v[160:163], v155 offset:2048
	ds_read_b128 v[164:167], v155 offset:3072
	v_add_u32_e32 v155, s67, v149
	ds_read_b128 v[168:171], v155
	ds_read_b128 v[172:175], v155 offset:1024
	ds_read_b128 v[176:179], v155 offset:2048
	ds_read_b128 v[180:183], v155 offset:3072
	s_add_u32 s36, s36, 0x40000
	s_addc_u32 s37, s37, 0
	s_mov_b32 m0, s43
	v_lshl_add_u64 v[224:225], s[36:37], 0, v[134:135]
	ds_read_b128 v[184:187], v153 offset:32768
	ds_read_b128 v[188:191], v153 offset:33792
	ds_read_b128 v[192:195], v153 offset:34816
	ds_read_b128 v[196:199], v153 offset:35840
	ds_read_b128 v[200:203], v153 offset:36864
	ds_read_b128 v[204:207], v153 offset:37888
	ds_read_b128 v[208:211], v153 offset:38912
	ds_read_b128 v[212:215], v153 offset:39936
	global_load_lds_dwordx4 v[224:225], off
	v_lshl_add_u64 v[224:225], s[36:37], 0, v[130:131]
	s_mov_b32 m0, s46
	s_nop 0
	global_load_lds_dwordx4 v[224:225], off
	s_cmp_eq_u32 s99, 1
	s_cbranch_scc1 .Lrw_P5_2
	s_waitcnt vmcnt(8)
	s_branch .Lrj_P5_2

; #define PG8_STAGE(bufoff, gbase, voff) do { _Pragma("unroll") for (int _i = 0; _i < 2; ++_i) \
;         __builtin_amdgcn_global_load_lds((const unsigned*)((const char*)(gbase) + (voff)[_i]), (PG8_LAS unsigned*)(lds + (bufoff) + ldsw + _i * 8192), 16, 0, 0); } while (0)
; #define PG8_LDA(dst, b, h) do { _Pragma("unroll") for (int m = 0; m < 4; ++m) _Pragma("unroll") for (int k = 0; k < 2; ++k) dst[m][k] = *(const PG8_LAS bf16x8*)(lds + PG8_SA(b, h) + aoff + m * 2048 + k * 1024); } while (0)
; #define PG8_MMA(ai, bj, At, Bt) do { __builtin_amdgcn_s_setprio(1); _Pragma("unroll") for (int m = 0; m < 4; ++m) _Pragma("unroll") for (int n = 0; n < 2; ++n) _Pragma("unroll") for (int k = 0; k < 2; ++k) \
;         acc[ai][bj][m][n] = __builtin_amdgcn_mfma_f32_16x16x32_bf16(Bt[n][k], At[m][k], acc[ai][bj][m][n], 0, 0, 0); __builtin_amdgcn_s_setprio(0); } while (0)
; #define PG8_WAIT_V(n) asm volatile("s_waitcnt vmcnt(" #n ")" ::: "memory")
; #define PG8_WAIT_L(n) asm volatile("s_waitcnt lgkmcnt(" #n ")" ::: "memory")
; #define PG8_BAR __builtin_amdgcn_s_barrier()
; #define PG8_SCHED __builtin_amdgcn_sched_barrier(0)
; template <class Epi, class Sched, bool ALIGN_EPI = false, bool SP2 = false>
; __device__ __forceinline__ void gemm_phase(PG8_LAS unsigned char* lds, const Gemm g, const Sched& S, const Epi& E) {
;     ...
;             PG8_LDA(At, 1, 1); PG8_STAGE(PG8_SB(1, 0), b3, voffB); PG8_STAGE(PG8_SB(1, 1), b3 + hstep, voffB); PG8_STAGE(PG8_SA(1, 0), a3, voffA);
;             PG8_WAIT_V(8); PG8_WAIT_L(0); PG8_BAR; PG8_MMA(1, 0, At, B0); PG8_MMA(1, 1, At, B1); PG8_BAR; PG8_SCHED;
;     __device__ __forceinline__ void operator()(const f32x4 (&acc)[2][2][4][2], const Unit& u, int wr, int wc, int fr, int fq) const {
;     ...
;             for (int m = 0; m < 4; ++m) { const int row = rbase + ai * 128 + m * 16; const f32x4* sp = (const f32x4*)(SSP + (size_t)row * 16);
;                 const f32x4 s4 = (sp[0] + sp[1]) + (sp[2] + sp[3]); const float rstd = __builtin_amdgcn_rsqf(((s4[0] + s4[1]) + (s4[2] + s4[3])) * (1.0f / 1024.0f) + EPS);
.Lrj_P5_3:
	s_waitcnt lgkmcnt(0)
	s_barrier
	s_cmp_eq_u32 s65, 12
	s_cbranch_scc0 .Lessp_skip
	v_lshl_add_u32 v252, s28, 8, v148
	v_bfe_u32 v253, v226, 4, 2
	v_lshlrev_b32_e32 v252, 6, v252
	v_lshl_add_u32 v252, v253, 4, v252
	v_add_u32_e32 v253, 0x2000, v252
	global_load_dwordx4 v[228:231], v252, s[12:13]
	global_load_dwordx4 v[232:235], v252, s[12:13] offset:1024
	global_load_dwordx4 v[236:239], v252, s[12:13] offset:2048
	global_load_dwordx4 v[240:243], v252, s[12:13] offset:3072
	global_load_dwordx4 v[244:247], v253, s[12:13]
	global_load_dwordx4 v[248:251], v253, s[12:13] offset:1024

; __device__ __forceinline__ u32x4 pack8(const f32x4 a, const f32x4 b) { u32x4 w; w.x = cvt_pk_bf16(a[0], a[1]); w.y = cvt_pk_bf16(a[2], a[3]); w.z = cvt_pk_bf16(b[0], b[1]); w.w = cvt_pk_bf16(b[2], b[3]); return w; }
;     __device__ __forceinline__ void operator()(const f32x4 (&acc)[2][2][4][2], const Unit& u, int wr, int wc, int fr, int fq) const {
;     ...
;             for (int m = 0; m < 4; ++m) { const int row = rbase + ai * 128 + m * 16; const f32x4* sp = (const f32x4*)(SSP + (size_t)row * 16);
;                 const f32x4 s4 = (sp[0] + sp[1]) + (sp[2] + sp[3]); const float rstd = __builtin_amdgcn_rsqf(((s4[0] + s4[1]) + (s4[2] + s4[3])) * (1.0f / 1024.0f) + EPS);
; #pragma unroll
;                 for (int bj = 0; bj < 2; ++bj) { f32x4 v0 = acc[ai][bj][m][0] * rstd, v1 = acc[ai][bj][m][1] * rstd;
; #pragma unroll
;                     for (int i = 0; i < 4; ++i) { const float a = fmaxf(v0[i], 0.f), b = fmaxf(v1[i], 0.f); v0[i] = a * a; v1[i] = b * b; }
;                     *(u32x4*)(Z + (size_t)row * FF + cb + bj * 128) = pack8(v0, v1); }
.LBB0_1543:
	v_lshlrev_b64 v[220:221], 13, v[146:147]
	v_lshl_or_b32 v222, s60, 8, v150
	v_ashrrev_i32_e32 v223, 31, v222
	v_lshlrev_b64 v[222:223], 1, v[222:223]
	v_lshl_add_u32 v227, v146, 13, v222
	v_lshl_add_u64 v[220:221], s[8:9], 0, v[220:221]
	v_lshl_add_u64 v[220:221], v[220:221], 0, v[222:223]
	s_mov_b64 s[100:101], 0xa0000
	s_mov_b64 s[98:99], 0x20000
	s_waitcnt vmcnt(4)
	v_pk_add_f32 v[228:229], v[228:229], v[230:231]
	v_pk_add_f32 v[232:233], v[232:233], v[234:235]
	v_pk_add_f32 v[236:237], v[236:237], v[238:239]
	v_pk_add_f32 v[240:241], v[240:241], v[242:243]
	v_add_f32_e32 v228, v228, v229
	v_add_f32_e32 v232, v232, v233
	v_add_f32_e32 v236, v236, v237
	v_add_f32_e32 v240, v240, v241
	v_mov_b32_e32 v229, v228
	v_mov_b32_e32 v233, v232
	v_mov_b32_e32 v237, v236
	v_mov_b32_e32 v241, v240
	s_nop 1
	v_permlane16_swap_b32_e32 v229, v228
	v_permlane16_swap_b32_e32 v233, v232
	v_permlane16_swap_b32_e32 v237, v236
	v_permlane16_swap_b32_e32 v241, v240
	s_nop 1
	v_add_f32_e32 v228, v228, v229
	v_add_f32_e32 v232, v232, v233
	v_add_f32_e32 v236, v236, v237
	v_add_f32_e32 v240, v240, v241
	v_mov_b32_e32 v229, v228
	v_mov_b32_e32 v233, v232
	v_mov_b32_e32 v237, v236
	v_mov_b32_e32 v241, v240
	s_nop 1
	v_permlane32_swap_b32_e32 v229, v228
	v_permlane32_swap_b32_e32 v233, v232
	v_permlane32_swap_b32_e32 v237, v236
	v_permlane32_swap_b32_e32 v241, v240
	s_nop 1
	v_add_f32_e32 v228, v228, v229
	v_add_f32_e32 v232, v232, v233
	v_add_f32_e32 v236, v236, v237
	v_add_f32_e32 v240, v240, v241
	v_fmamk_f32 v228, v228, 0x3a800000, v154
	v_fmamk_f32 v232, v232, 0x3a800000, v154
	v_fmamk_f32 v236, v236, 0x3a800000, v154
	v_fmamk_f32 v240, v240, 0x3a800000, v154
	v_rsq_f32_e32 v228, v228
	v_rsq_f32_e32 v232, v232
	v_rsq_f32_e32 v236, v236
	v_rsq_f32_e32 v240, v240
	s_nop 0
	v_pk_mul_f32 v[112:113], v[112:113], v[228:229] op_sel_hi:[1,0]
	v_pk_mul_f32 v[114:115], v[114:115], v[228:229] op_sel_hi:[1,0]
	v_pk_mul_f32 v[116:117], v[116:117], v[228:229] op_sel_hi:[1,0]
	v_pk_mul_f32 v[118:119], v[118:119], v[228:229] op_sel_hi:[1,0]
	v_pk_mul_f32 v[120:121], v[120:121], v[228:229] op_sel_hi:[1,0]
	v_pk_mul_f32 v[122:123], v[122:123], v[228:229] op_sel_hi:[1,0]
	v_pk_mul_f32 v[124:125], v[124:125], v[228:229] op_sel_hi:[1,0]
	v_pk_mul_f32 v[126:127], v[126:127], v[228:229] op_sel_hi:[1,0]
	v_max_f32_e32 v112, 0, v112
	v_max_f32_e32 v113, 0, v113
	v_max_f32_e32 v114, 0, v114
	v_max_f32_e32 v115, 0, v115
	v_max_f32_e32 v116, 0, v116
	v_max_f32_e32 v117, 0, v117
	v_max_f32_e32 v118, 0, v118
	v_max_f32_e32 v119, 0, v119
	v_max_f32_e32 v120, 0, v120
	v_max_f32_e32 v121, 0, v121
	v_max_f32_e32 v122, 0, v122
	v_max_f32_e32 v123, 0, v123
	v_max_f32_e32 v124, 0, v124
	v_max_f32_e32 v125, 0, v125
	v_max_f32_e32 v126, 0, v126
	v_max_f32_e32 v127, 0, v127
	v_pk_mul_f32 v[112:113], v[112:113], v[112:113]
	v_pk_mul_f32 v[114:115], v[114:115], v[114:115]
	v_pk_mul_f32 v[116:117], v[116:117], v[116:117]
	v_pk_mul_f32 v[118:119], v[118:119], v[118:119]
	v_pk_mul_f32 v[120:121], v[120:121], v[120:121]
	v_pk_mul_f32 v[122:123], v[122:123], v[122:123]
	v_pk_mul_f32 v[124:125], v[124:125], v[124:125]
	v_pk_mul_f32 v[126:127], v[126:127], v[126:127]
	v_cvt_pk_bf16_f32 v124, v124, v125
	v_cvt_pk_bf16_f32 v125, v126, v127
	v_cvt_pk_bf16_f32 v126, v120, v121
	v_cvt_pk_bf16_f32 v127, v122, v123
	v_cvt_pk_bf16_f32 v116, v116, v117
	v_cvt_pk_bf16_f32 v117, v118, v119
	v_cvt_pk_bf16_f32 v118, v112, v113
	v_cvt_pk_bf16_f32 v119, v114, v115
	global_store_dwordx4 v[220:221], v[124:127], off
	global_store_dwordx4 v[220:221], v[116:119], off offset:256
	v_lshl_add_u64 v[220:221], v[220:221], 0, s[98:99]
	v_pk_mul_f32 v[96:97], v[96:97], v[232:233] op_sel_hi:[1,0]
	v_pk_mul_f32 v[98:99], v[98:99], v[232:233] op_sel_hi:[1,0]
	v_pk_mul_f32 v[100:101], v[100:101], v[232:233] op_sel_hi:[1,0]
	v_pk_mul_f32 v[102:103], v[102:103], v[232:233] op_sel_hi:[1,0]
	v_pk_mul_f32 v[104:105], v[104:105], v[232:233] op_sel_hi:[1,0]
	v_pk_mul_f32 v[106:107], v[106:107], v[232:233] op_sel_hi:[1,0]
	v_pk_mul_f32 v[108:109], v[108:109], v[232:233] op_sel_hi:[1,0]
	v_pk_mul_f32 v[110:111], v[110:111], v[232:233] op_sel_hi:[1,0]
	v_max_f32_e32 v96, 0, v96
	v_max_f32_e32 v97, 0, v97
	v_max_f32_e32 v98, 0, v98
	v_max_f32_e32 v99, 0, v99
	v_max_f32_e32 v100, 0, v100
	v_max_f32_e32 v101, 0, v101
	v_max_f32_e32 v102, 0, v102
	v_max_f32_e32 v103, 0, v103
	v_max_f32_e32 v104, 0, v104
	v_max_f32_e32 v105, 0, v105
	v_max_f32_e32 v106, 0, v106
	v_max_f32_e32 v107, 0, v107
	v_max_f32_e32 v108, 0, v108
	v_max_f32_e32 v109, 0, v109
	v_max_f32_e32 v110, 0, v110
	v_max_f32_e32 v111, 0, v111
	v_pk_mul_f32 v[96:97], v[96:97], v[96:97]
	v_pk_mul_f32 v[98:99], v[98:99], v[98:99]
	v_pk_mul_f32 v[100:101], v[100:101], v[100:101]
	v_pk_mul_f32 v[102:103], v[102:103], v[102:103]
	v_pk_mul_f32 v[104:105], v[104:105], v[104:105]
	v_pk_mul_f32 v[106:107], v[106:107], v[106:107]
	v_pk_mul_f32 v[108:109], v[108:109], v[108:109]
	v_pk_mul_f32 v[110:111], v[110:111], v[110:111]
	v_cvt_pk_bf16_f32 v108, v108, v109
	v_cvt_pk_bf16_f32 v109, v110, v111
	v_cvt_pk_bf16_f32 v110, v104, v105
	v_cvt_pk_bf16_f32 v111, v106, v107
	v_cvt_pk_bf16_f32 v100, v100, v101
	v_cvt_pk_bf16_f32 v101, v102, v103
	v_cvt_pk_bf16_f32 v102, v96, v97
	v_cvt_pk_bf16_f32 v103, v98, v99
	global_store_dwordx4 v[220:221], v[108:111], off
	global_store_dwordx4 v[220:221], v[100:103], off offset:256
	v_lshl_add_u64 v[220:221], v[220:221], 0, s[98:99]
	v_pk_mul_f32 v[80:81], v[80:81], v[236:237] op_sel_hi:[1,0]
	v_pk_mul_f32 v[82:83], v[82:83], v[236:237] op_sel_hi:[1,0]
	v_pk_mul_f32 v[84:85], v[84:85], v[236:237] op_sel_hi:[1,0]
	v_pk_mul_f32 v[86:87], v[86:87], v[236:237] op_sel_hi:[1,0]
; __device__ __forceinline__ u32x4 pack8(const f32x4 a, const f32x4 b) { u32x4 w; w.x = cvt_pk_bf16(a[0], a[1]); w.y = cvt_pk_bf16(a[2], a[3]); w.z = cvt_pk_bf16(b[0], b[1]); w.w = cvt_pk_bf16(b[2], b[3]); return w; }
;     __device__ __forceinline__ void operator()(const f32x4 (&acc)[2][2][4][2], const Unit& u, int wr, int wc, int fr, int fq) const {
;     ...
;             for (int m = 0; m < 4; ++m) { const int row = rbase + ai * 128 + m * 16; const f32x4* sp = (const f32x4*)(SSP + (size_t)row * 16);
;                 const f32x4 s4 = (sp[0] + sp[1]) + (sp[2] + sp[3]); const float rstd = __builtin_amdgcn_rsqf(((s4[0] + s4[1]) + (s4[2] + s4[3])) * (1.0f / 1024.0f) + EPS);
; #pragma unroll
;                 for (int bj = 0; bj < 2; ++bj) { f32x4 v0 = acc[ai][bj][m][0] * rstd, v1 = acc[ai][bj][m][1] * rstd;
; #pragma unroll
;                     for (int i = 0; i < 4; ++i) { const float a = fmaxf(v0[i], 0.f), b = fmaxf(v1[i], 0.f); v0[i] = a * a; v1[i] = b * b; }
;                     *(u32x4*)(Z + (size_t)row * FF + cb + bj * 128) = pack8(v0, v1); }
	v_pk_mul_f32 v[88:89], v[88:89], v[236:237] op_sel_hi:[1,0]
	v_pk_mul_f32 v[90:91], v[90:91], v[236:237] op_sel_hi:[1,0]
	v_pk_mul_f32 v[92:93], v[92:93], v[236:237] op_sel_hi:[1,0]
	v_pk_mul_f32 v[94:95], v[94:95], v[236:237] op_sel_hi:[1,0]
	v_max_f32_e32 v80, 0, v80
	v_max_f32_e32 v81, 0, v81
	v_max_f32_e32 v82, 0, v82
	v_max_f32_e32 v83, 0, v83
	v_max_f32_e32 v84, 0, v84
	v_max_f32_e32 v85, 0, v85
	v_max_f32_e32 v86, 0, v86
	v_max_f32_e32 v87, 0, v87
	v_max_f32_e32 v88, 0, v88
	v_max_f32_e32 v89, 0, v89
	v_max_f32_e32 v90, 0, v90
	v_max_f32_e32 v91, 0, v91
	v_max_f32_e32 v92, 0, v92
	v_max_f32_e32 v93, 0, v93
	v_max_f32_e32 v94, 0, v94
	v_max_f32_e32 v95, 0, v95
	v_pk_mul_f32 v[80:81], v[80:81], v[80:81]
	v_pk_mul_f32 v[82:83], v[82:83], v[82:83]
	v_pk_mul_f32 v[84:85], v[84:85], v[84:85]
	v_pk_mul_f32 v[86:87], v[86:87], v[86:87]
	v_pk_mul_f32 v[88:89], v[88:89], v[88:89]
	v_pk_mul_f32 v[90:91], v[90:91], v[90:91]
	v_pk_mul_f32 v[92:93], v[92:93], v[92:93]
	v_pk_mul_f32 v[94:95], v[94:95], v[94:95]
	v_cvt_pk_bf16_f32 v92, v92, v93
	v_cvt_pk_bf16_f32 v93, v94, v95
	v_cvt_pk_bf16_f32 v94, v88, v89
	v_cvt_pk_bf16_f32 v95, v90, v91
	v_cvt_pk_bf16_f32 v84, v84, v85
	v_cvt_pk_bf16_f32 v85, v86, v87
	v_cvt_pk_bf16_f32 v86, v80, v81
	v_cvt_pk_bf16_f32 v87, v82, v83
	global_store_dwordx4 v[220:221], v[92:95], off
	global_store_dwordx4 v[220:221], v[84:87], off offset:256
	v_lshl_add_u64 v[220:221], v[220:221], 0, s[98:99]
	v_pk_mul_f32 v[64:65], v[64:65], v[240:241] op_sel_hi:[1,0]
	v_pk_mul_f32 v[66:67], v[66:67], v[240:241] op_sel_hi:[1,0]
	v_pk_mul_f32 v[68:69], v[68:69], v[240:241] op_sel_hi:[1,0]
	v_pk_mul_f32 v[70:71], v[70:71], v[240:241] op_sel_hi:[1,0]
	v_pk_mul_f32 v[72:73], v[72:73], v[240:241] op_sel_hi:[1,0]
	v_pk_mul_f32 v[74:75], v[74:75], v[240:241] op_sel_hi:[1,0]
	v_pk_mul_f32 v[76:77], v[76:77], v[240:241] op_sel_hi:[1,0]
	v_pk_mul_f32 v[78:79], v[78:79], v[240:241] op_sel_hi:[1,0]
	v_max_f32_e32 v64, 0, v64
	v_max_f32_e32 v65, 0, v65
	v_max_f32_e32 v66, 0, v66
	v_max_f32_e32 v67, 0, v67
	v_max_f32_e32 v68, 0, v68
	v_max_f32_e32 v69, 0, v69
	v_max_f32_e32 v70, 0, v70
	v_max_f32_e32 v71, 0, v71
	v_max_f32_e32 v72, 0, v72
	v_max_f32_e32 v73, 0, v73
	v_max_f32_e32 v74, 0, v74
	v_max_f32_e32 v75, 0, v75
	v_max_f32_e32 v76, 0, v76
	v_max_f32_e32 v77, 0, v77
	v_max_f32_e32 v78, 0, v78
	v_max_f32_e32 v79, 0, v79
	v_pk_mul_f32 v[64:65], v[64:65], v[64:65]
	v_pk_mul_f32 v[66:67], v[66:67], v[66:67]
	v_pk_mul_f32 v[68:69], v[68:69], v[68:69]
	v_pk_mul_f32 v[70:71], v[70:71], v[70:71]
	v_pk_mul_f32 v[72:73], v[72:73], v[72:73]
	v_pk_mul_f32 v[74:75], v[74:75], v[74:75]
	v_pk_mul_f32 v[76:77], v[76:77], v[76:77]
	v_pk_mul_f32 v[78:79], v[78:79], v[78:79]
	v_cvt_pk_bf16_f32 v76, v76, v77
	v_cvt_pk_bf16_f32 v77, v78, v79
	v_cvt_pk_bf16_f32 v78, v72, v73
	v_cvt_pk_bf16_f32 v79, v74, v75
	v_cvt_pk_bf16_f32 v68, v68, v69
	v_cvt_pk_bf16_f32 v69, v70, v71
	v_cvt_pk_bf16_f32 v70, v64, v65
	v_cvt_pk_bf16_f32 v71, v66, v67
	global_store_dwordx4 v[220:221], v[76:79], off
	global_store_dwordx4 v[220:221], v[68:71], off offset:256
	v_lshl_add_u64 v[220:221], v[220:221], 0, s[100:101]
	s_waitcnt vmcnt(8)
	v_pk_add_f32 v[244:245], v[244:245], v[246:247]
	v_pk_add_f32 v[248:249], v[248:249], v[250:251]
	v_pk_add_f32 v[180:181], v[180:181], v[182:183]
	v_pk_add_f32 v[184:185], v[184:185], v[186:187]
	v_add_f32_e32 v244, v244, v245
	v_add_f32_e32 v248, v248, v249
	v_add_f32_e32 v180, v180, v181
	v_add_f32_e32 v184, v184, v185
	v_mov_b32_e32 v245, v244
	v_mov_b32_e32 v249, v248
	v_mov_b32_e32 v181, v180
	v_mov_b32_e32 v185, v184
	s_nop 1
	v_permlane16_swap_b32_e32 v245, v244
	v_permlane16_swap_b32_e32 v249, v248
	v_permlane16_swap_b32_e32 v181, v180
	v_permlane16_swap_b32_e32 v185, v184
	s_nop 1
	v_add_f32_e32 v244, v244, v245
	v_add_f32_e32 v248, v248, v249
	v_add_f32_e32 v180, v180, v181
	v_add_f32_e32 v184, v184, v185
	v_mov_b32_e32 v245, v244
	v_mov_b32_e32 v249, v248
	v_mov_b32_e32 v181, v180
	v_mov_b32_e32 v185, v184
	s_nop 1
	v_permlane32_swap_b32_e32 v245, v244
	v_permlane32_swap_b32_e32 v249, v248
	v_permlane32_swap_b32_e32 v181, v180
	v_permlane32_swap_b32_e32 v185, v184
	s_nop 1
	v_add_f32_e32 v244, v244, v245
	v_add_f32_e32 v248, v248, v249
	v_add_f32_e32 v180, v180, v181
	v_add_f32_e32 v184, v184, v185
	v_fmamk_f32 v244, v244, 0x3a800000, v154
	v_fmamk_f32 v248, v248, 0x3a800000, v154
	v_fmamk_f32 v180, v180, 0x3a800000, v154
	v_fmamk_f32 v184, v184, 0x3a800000, v154
	v_rsq_f32_e32 v244, v244
	v_rsq_f32_e32 v248, v248
	v_rsq_f32_e32 v180, v180
	v_rsq_f32_e32 v184, v184
	s_nop 0
	v_pk_mul_f32 v[48:49], v[48:49], v[244:245] op_sel_hi:[1,0]
	v_pk_mul_f32 v[50:51], v[50:51], v[244:245] op_sel_hi:[1,0]
	v_pk_mul_f32 v[52:53], v[52:53], v[244:245] op_sel_hi:[1,0]
	v_pk_mul_f32 v[54:55], v[54:55], v[244:245] op_sel_hi:[1,0]
	v_pk_mul_f32 v[56:57], v[56:57], v[244:245] op_sel_hi:[1,0]
	v_pk_mul_f32 v[58:59], v[58:59], v[244:245] op_sel_hi:[1,0]
	v_pk_mul_f32 v[60:61], v[60:61], v[244:245] op_sel_hi:[1,0]
	v_pk_mul_f32 v[62:63], v[62:63], v[244:245] op_sel_hi:[1,0]
	v_max_f32_e32 v48, 0, v48
	v_max_f32_e32 v49, 0, v49
	v_max_f32_e32 v50, 0, v50
	v_max_f32_e32 v51, 0, v51
	v_max_f32_e32 v52, 0, v52
	v_max_f32_e32 v53, 0, v53
	v_max_f32_e32 v54, 0, v54
	v_max_f32_e32 v55, 0, v55
	v_max_f32_e32 v56, 0, v56
	v_max_f32_e32 v57, 0, v57
	v_max_f32_e32 v58, 0, v58
	v_max_f32_e32 v59, 0, v59
	v_max_f32_e32 v60, 0, v60
	v_max_f32_e32 v61, 0, v61
	v_max_f32_e32 v62, 0, v62
	v_max_f32_e32 v63, 0, v63
	v_pk_mul_f32 v[48:49], v[48:49], v[48:49]
	v_pk_mul_f32 v[50:51], v[50:51], v[50:51]
	v_pk_mul_f32 v[52:53], v[52:53], v[52:53]
	v_pk_mul_f32 v[54:55], v[54:55], v[54:55]
; #define PG8_BAR __builtin_amdgcn_s_barrier()
; __device__ __forceinline__ u32x4 pack8(const f32x4 a, const f32x4 b) { u32x4 w; w.x = cvt_pk_bf16(a[0], a[1]); w.y = cvt_pk_bf16(a[2], a[3]); w.z = cvt_pk_bf16(b[0], b[1]); w.w = cvt_pk_bf16(b[2], b[3]); return w; }
; template <class Epi, class Sched, bool ALIGN_EPI = false, bool SP2 = false>
; __device__ __forceinline__ void gemm_phase(PG8_LAS unsigned char* lds, const Gemm g, const Sched& S, const Epi& E) {
;     ...
;         if (!has_next) break;
; #pragma unroll
;         for (int a = 0; a < 2; ++a)
; #pragma unroll
;             for (int b = 0; b < 2; ++b)
; #pragma unroll
;                 for (int m = 0; m < 4; ++m)
; #pragma unroll
;                     for (int n = 0; n < 2; ++n) acc[a][b][m][n] = (f32x4){0.f, 0.f, 0.f, 0.f};
;         cur = nxt; cA = nA; cB = nB; ++ui;
;         if constexpr (ALIGN_EPI) { if (wr == 1) PG8_BAR; }
;     __device__ __forceinline__ void operator()(const f32x4 (&acc)[2][2][4][2], const Unit& u, int wr, int wc, int fr, int fq) const {
;     ...
;             for (int m = 0; m < 4; ++m) { const int row = rbase + ai * 128 + m * 16; const f32x4* sp = (const f32x4*)(SSP + (size_t)row * 16);
;                 const f32x4 s4 = (sp[0] + sp[1]) + (sp[2] + sp[3]); const float rstd = __builtin_amdgcn_rsqf(((s4[0] + s4[1]) + (s4[2] + s4[3])) * (1.0f / 1024.0f) + EPS);
; #pragma unroll
;                 for (int bj = 0; bj < 2; ++bj) { f32x4 v0 = acc[ai][bj][m][0] * rstd, v1 = acc[ai][bj][m][1] * rstd;
; #pragma unroll
;                     for (int i = 0; i < 4; ++i) { const float a = fmaxf(v0[i], 0.f), b = fmaxf(v1[i], 0.f); v0[i] = a * a; v1[i] = b * b; }
;                     *(u32x4*)(Z + (size_t)row * FF + cb + bj * 128) = pack8(v0, v1); }
	v_pk_mul_f32 v[56:57], v[56:57], v[56:57]
	v_pk_mul_f32 v[58:59], v[58:59], v[58:59]
	v_pk_mul_f32 v[60:61], v[60:61], v[60:61]
	v_pk_mul_f32 v[62:63], v[62:63], v[62:63]
	v_cvt_pk_bf16_f32 v60, v60, v61
	v_cvt_pk_bf16_f32 v61, v62, v63
	v_cvt_pk_bf16_f32 v62, v56, v57
	v_cvt_pk_bf16_f32 v63, v58, v59
	v_cvt_pk_bf16_f32 v52, v52, v53
	v_cvt_pk_bf16_f32 v53, v54, v55
	v_cvt_pk_bf16_f32 v54, v48, v49
	v_cvt_pk_bf16_f32 v55, v50, v51
	global_store_dwordx4 v[220:221], v[60:63], off
	global_store_dwordx4 v[220:221], v[52:55], off offset:256
	v_lshl_add_u64 v[220:221], v[220:221], 0, s[98:99]
	v_mul_f32_e32 v32, v248, v32
	v_mul_f32_e32 v33, v248, v33
	v_mul_f32_e32 v34, v248, v34
	v_mul_f32_e32 v35, v248, v35
	v_mul_f32_e32 v36, v248, v36
	v_mul_f32_e32 v37, v248, v37
	v_mul_f32_e32 v38, v248, v38
	v_mul_f32_e32 v39, v248, v39
	v_mul_f32_e32 v40, v248, v40
	v_mul_f32_e32 v41, v248, v41
	v_mul_f32_e32 v42, v248, v42
	v_mul_f32_e32 v43, v248, v43
	v_mul_f32_e32 v44, v248, v44
	v_mul_f32_e32 v45, v248, v45
	v_mul_f32_e32 v46, v248, v46
	v_mul_f32_e32 v47, v248, v47
	v_max_f32_e32 v32, 0, v32
	v_max_f32_e32 v33, 0, v33
	v_max_f32_e32 v34, 0, v34
	v_max_f32_e32 v35, 0, v35
	v_max_f32_e32 v36, 0, v36
	v_max_f32_e32 v37, 0, v37
	v_max_f32_e32 v38, 0, v38
	v_max_f32_e32 v39, 0, v39
	v_max_f32_e32 v40, 0, v40
	v_max_f32_e32 v41, 0, v41
	v_max_f32_e32 v42, 0, v42
	v_max_f32_e32 v43, 0, v43
	v_max_f32_e32 v44, 0, v44
	v_max_f32_e32 v45, 0, v45
	v_max_f32_e32 v46, 0, v46
	v_max_f32_e32 v47, 0, v47
	v_mul_f32_e32 v32, v32, v32
	v_mul_f32_e32 v33, v33, v33
	v_mul_f32_e32 v34, v34, v34
	v_mul_f32_e32 v35, v35, v35
	v_mul_f32_e32 v36, v36, v36
	v_mul_f32_e32 v37, v37, v37
	v_mul_f32_e32 v38, v38, v38
	v_mul_f32_e32 v39, v39, v39
	v_mul_f32_e32 v40, v40, v40
	v_mul_f32_e32 v41, v41, v41
	v_mul_f32_e32 v42, v42, v42
	v_mul_f32_e32 v43, v43, v43
	v_mul_f32_e32 v44, v44, v44
	v_mul_f32_e32 v45, v45, v45
	v_mul_f32_e32 v46, v46, v46
	v_mul_f32_e32 v47, v47, v47
	v_cvt_pk_bf16_f32 v228, v44, v45
	v_cvt_pk_bf16_f32 v229, v46, v47
	v_cvt_pk_bf16_f32 v230, v40, v41
	v_cvt_pk_bf16_f32 v231, v42, v43
	v_cvt_pk_bf16_f32 v232, v36, v37
	v_cvt_pk_bf16_f32 v233, v38, v39
	v_cvt_pk_bf16_f32 v234, v32, v33
	v_cvt_pk_bf16_f32 v235, v34, v35
	v_mul_f32_e32 v16, v180, v16
	v_mul_f32_e32 v17, v180, v17
	v_mul_f32_e32 v18, v180, v18
	v_mul_f32_e32 v19, v180, v19
	v_mul_f32_e32 v20, v180, v20
	v_mul_f32_e32 v21, v180, v21
	v_mul_f32_e32 v22, v180, v22
	v_mul_f32_e32 v23, v180, v23
	v_mul_f32_e32 v24, v180, v24
	v_mul_f32_e32 v25, v180, v25
	v_mul_f32_e32 v26, v180, v26
	v_mul_f32_e32 v27, v180, v27
	v_mul_f32_e32 v28, v180, v28
	v_mul_f32_e32 v29, v180, v29
	v_mul_f32_e32 v30, v180, v30
	v_mul_f32_e32 v31, v180, v31
	v_max_f32_e32 v16, 0, v16
	v_max_f32_e32 v17, 0, v17
	v_max_f32_e32 v18, 0, v18
	v_max_f32_e32 v19, 0, v19
	v_max_f32_e32 v20, 0, v20
	v_max_f32_e32 v21, 0, v21
	v_max_f32_e32 v22, 0, v22
	v_max_f32_e32 v23, 0, v23
	v_max_f32_e32 v24, 0, v24
	v_max_f32_e32 v25, 0, v25
	v_max_f32_e32 v26, 0, v26
	v_max_f32_e32 v27, 0, v27
	v_max_f32_e32 v28, 0, v28
	v_max_f32_e32 v29, 0, v29
	v_max_f32_e32 v30, 0, v30
	v_max_f32_e32 v31, 0, v31
	v_mul_f32_e32 v16, v16, v16
	v_mul_f32_e32 v17, v17, v17
	v_mul_f32_e32 v18, v18, v18
	v_mul_f32_e32 v19, v19, v19
	v_mul_f32_e32 v20, v20, v20
	v_mul_f32_e32 v21, v21, v21
	v_mul_f32_e32 v22, v22, v22
	v_mul_f32_e32 v23, v23, v23
	v_mul_f32_e32 v24, v24, v24
	v_mul_f32_e32 v25, v25, v25
	v_mul_f32_e32 v26, v26, v26
	v_mul_f32_e32 v27, v27, v27
	v_mul_f32_e32 v28, v28, v28
	v_mul_f32_e32 v29, v29, v29
	v_mul_f32_e32 v30, v30, v30
	v_mul_f32_e32 v31, v31, v31
	v_cvt_pk_bf16_f32 v236, v28, v29
	v_cvt_pk_bf16_f32 v237, v30, v31
	v_cvt_pk_bf16_f32 v238, v24, v25
	v_cvt_pk_bf16_f32 v239, v26, v27
	v_cvt_pk_bf16_f32 v240, v20, v21
	v_cvt_pk_bf16_f32 v241, v22, v23
	v_cvt_pk_bf16_f32 v242, v16, v17
	v_cvt_pk_bf16_f32 v243, v18, v19
	v_mul_f32_e32 v0, v184, v0
	v_mul_f32_e32 v1, v184, v1
	v_mul_f32_e32 v2, v184, v2
	v_mul_f32_e32 v3, v184, v3
	v_mul_f32_e32 v4, v184, v4
	v_mul_f32_e32 v5, v184, v5
	v_mul_f32_e32 v6, v184, v6
	v_mul_f32_e32 v7, v184, v7
	v_mul_f32_e32 v8, v184, v8
	v_mul_f32_e32 v9, v184, v9
	v_mul_f32_e32 v10, v184, v10
	v_mul_f32_e32 v11, v184, v11
	v_mul_f32_e32 v12, v184, v12
	v_mul_f32_e32 v13, v184, v13
	v_mul_f32_e32 v14, v184, v14
	v_mul_f32_e32 v15, v184, v15
	v_max_f32_e32 v0, 0, v0
	v_max_f32_e32 v1, 0, v1
	v_max_f32_e32 v2, 0, v2
	v_max_f32_e32 v3, 0, v3
	v_max_f32_e32 v4, 0, v4
	v_max_f32_e32 v5, 0, v5
	v_max_f32_e32 v6, 0, v6
	v_max_f32_e32 v7, 0, v7
	v_max_f32_e32 v8, 0, v8
	v_max_f32_e32 v9, 0, v9
	v_max_f32_e32 v10, 0, v10
	v_max_f32_e32 v11, 0, v11
	v_max_f32_e32 v12, 0, v12
	v_max_f32_e32 v13, 0, v13
	v_max_f32_e32 v14, 0, v14
	v_max_f32_e32 v15, 0, v15
	v_mul_f32_e32 v0, v0, v0
	v_mul_f32_e32 v1, v1, v1
	v_mul_f32_e32 v2, v2, v2
	v_mul_f32_e32 v3, v3, v3
	v_mul_f32_e32 v4, v4, v4
	v_mul_f32_e32 v5, v5, v5
	v_mul_f32_e32 v6, v6, v6
	v_mul_f32_e32 v7, v7, v7
	v_mul_f32_e32 v8, v8, v8
	v_mul_f32_e32 v9, v9, v9
	v_mul_f32_e32 v10, v10, v10
	v_mul_f32_e32 v11, v11, v11
	v_mul_f32_e32 v12, v12, v12
	v_mul_f32_e32 v13, v13, v13
	v_mul_f32_e32 v14, v14, v14
	v_mul_f32_e32 v15, v15, v15
	v_cvt_pk_bf16_f32 v244, v12, v13
	v_cvt_pk_bf16_f32 v245, v14, v15
	v_cvt_pk_bf16_f32 v246, v8, v9
	v_cvt_pk_bf16_f32 v247, v10, v11
	v_cvt_pk_bf16_f32 v248, v4, v5
	v_cvt_pk_bf16_f32 v249, v6, v7
	v_cvt_pk_bf16_f32 v250, v0, v1
	v_cvt_pk_bf16_f32 v251, v2, v3
	s_andn2_b64 vcc, exec, s[4:5]
	s_mov_b64 s[4:5], -1
	s_cbranch_vccnz .LBB0_1536
	s_andn2_b64 vcc, exec, s[6:7]
	s_cbranch_vccnz .LBB0_1535
	s_barrier
	s_branch .LBB0_1535
